# adds: mixer phase unit assignment swaps waves 4-7 pairwise so each SIMD hosts one even and one odd query group (balances attention tile counts per SIMD)
# baseline (speedup 1.0000x reference)
; #define LAS __attribute__((address_space(3)))
; __global__ void __launch_bounds__(512, 2) fwd_kernel(Args a) {
;     ...
;     const int G = gridDim.x, NGW = G * 8;
;     const int wave0 = __builtin_amdgcn_readfirstlane((int)threadIdx.x >> 6);
;     ...
;     unsigned char* ws = a.ws;
;     const float* mod = (const float*)(ws + WS_MOD);
;     const bf16_t* Wgu = (const bf16_t*)(ws + WS_WGU); const bf16_t* Wd = (const bf16_t*)(ws + WS_WD); const bf16_t* Win = (const bf16_t*)(ws + WS_WIN);
;     const bf16_t* Wv = (const bf16_t*)(ws + WS_WV); const bf16_t* Wout = (const bf16_t*)(ws + WS_WOUT);
;     float* STATS = (float*)(ws + WS_STATS); float* SWB = (float*)(ws + WS_SW); bf16_t* MIX = (bf16_t*)(ws + WS_MIX); bf16_t* XB = (bf16_t*)(ws + WS_XB); LAS float* scr = (LAS float*)(lds + pg8::STAGE_BYTES);
;     bf16_t* H = (bf16_t*)(ws + WS_H); bf16_t* ACT = (bf16_t*)(ws + WS_ACT); bf16_t* PROJ = (bf16_t*)(ws + WS_PROJ); bf16_t* VT = (bf16_t*)(ws + WS_VT);
;     const int lo = a.lo, hi = a.hi;
;     int step = 0;
;     ...
;     volatile LAS unsigned* bst = (volatile LAS unsigned*)(lds + 8 * SB_WAVE_LDS);
;     if (threadIdx.x == 0) { bst[0] = 0u; bst[1] = 0u; }
;     unsigned* barw = (unsigned*)(ws + WS_CTL);
;     if (blockIdx.x == 0 && lo == 0) for (int i = threadIdx.x; i < XCD_BAR_WORDS; i += 512) __hip_atomic_store(barw + i, 0u, __ATOMIC_RELAXED, __HIP_MEMORY_SCOPE_AGENT);
;     __syncthreads();
;     XcdBarrier xb; xb.bar = barw; xb.x = 0; xb.st = bst;
;     ...
;     if (STEP_ON) { LANE_VARS; for (int rep = 0; rep < REP_PRO; ++rep) { prologue(a, lds, tid, lane, wave, gw, NGW); __syncthreads(); } }
;     STEP_END;
;     if (STEP_ON) { LANE_VARS;
;         for (int l = 0; l < NL; ++l) {
;             const float* modl = mod + (size_t)l * 8 * NMOD; float* sWl = SWB + (size_t)l * 8 * SW_ROWS;
;             sw_rows(Wgu + (size_t)(l * 2) * 5632 * 1024, 5632, modl, sWl + SW_GU1, gw, NGW, lane);
;             sw_rows(Win + (size_t)l * 2048 * 1024, 2048, modl + 3072, sWl + SW_IN, gw, NGW, lane);
;             sw_rows(Wv + (size_t)l * 512 * 1024, 512, modl + 3072, sWl + SW_V, gw, NGW, lane);
;             sw_rows(Wgu + (size_t)(l * 2 + 1) * 5632 * 1024, 5632, modl + 6144, sWl + SW_GU2, gw, NGW, lane);
;         }
;         init_xt(a.in[0], H, XB, STATS, a.in[4], mod + 1024, gw, NGW, lane);
;     }
;     STEP_END;
;     for (int l = 0; l < NL; ++l) {
.LBB0_150:
	v_writelane_b32 v252, s84, 38
	s_ashr_i32 s37, s2, 31
	s_lshr_b32 s0, s37, 29
	v_writelane_b32 v252, s85, 39
	v_writelane_b32 v252, s86, 40
	v_writelane_b32 v252, s87, 41
	v_writelane_b32 v252, s88, 42
	v_writelane_b32 v252, s89, 43
	v_writelane_b32 v252, s90, 44
	s_add_i32 s5, s2, s0
	v_writelane_b32 v252, s91, 45
	s_and_b32 s0, s5, -8
	v_writelane_b32 v252, s92, 46
	s_sub_i32 s7, s2, s0
	v_writelane_b32 v252, s93, 47
	s_lshl_b32 s0, s7, 6
	v_writelane_b32 v252, s94, 48
	s_cmp_lt_i32 s7, 0
	s_mul_i32 s1, s7, 0x41
	v_writelane_b32 v252, s95, 49
	s_cselect_b32 s4, s1, s0
	s_lshl_b32 s0, s7, 5
	v_writelane_b32 v252, s96, 50
	s_cmp_lt_i32 s7, 0
	s_mul_i32 s1, s7, 33
	v_writelane_b32 v252, s97, 51
	s_cselect_b32 s6, s1, s0
	s_lshl_b32 s0, s7, 7
	v_writelane_b32 v252, s98, 52
	s_cmp_lt_i32 s7, 0
	s_movk_i32 s15, 0x161
	s_mul_i32 s1, s7, 0x81
	v_writelane_b32 v252, s99, 53
	s_cselect_b32 s8, s15, 0x160
	s_cselect_b32 s0, s1, s0
	s_add_u32 s1, s26, 0x19300000
	v_writelane_b32 v252, s1, 54
	s_addc_u32 s1, s27, 0
	s_add_u32 s64, s26, 0x19600000
	s_addc_u32 s65, s27, 0
	s_add_u32 s16, s26, 0xe200000
	s_addc_u32 s17, s27, 0
	s_add_u32 s18, s26, 0x16200000
	v_writelane_b32 v252, s1, 55
	s_addc_u32 s19, s27, 0
	s_and_b32 s1, s81, 0xffffffc0
	s_cmpk_lt_i32 s2, 0xb00
	s_cselect_b64 s[10:11], -1, 0
	s_mul_i32 s8, s8, s7
	s_ashr_i32 s7, s5, 3
	s_add_i32 s8, s8, s7
	s_mul_hi_i32 s5, s8, 0x2e8ba2e9
	s_lshr_b32 s9, s5, 31
	s_ashr_i32 s5, s5, 5
	s_add_i32 s5, s5, s9
	s_mul_i32 s9, s5, 0xb0
	s_sub_i32 s9, s8, s9
	v_writelane_b32 v252, s10, 56
	s_bfe_u32 s8, s9, 0x3001c
	s_lshl_b32 s5, s5, 3
	v_writelane_b32 v252, s11, 57
	s_add_i32 s10, s9, s8
	s_sext_i32_i16 s11, s10
	s_and_b32 s10, s10, 0xfff8
	s_sub_i32 s9, s9, s10
	s_sext_i32_i16 s9, s9
	s_add_i32 s20, s5, s9
	s_ashr_i32 s5, s11, 3
	s_lshr_b32 s8, s11, 3
	v_writelane_b32 v252, s5, 58
	s_mov_b32 s10, s20
	v_writelane_b32 v252, s10, 59
	s_bfe_i64 s[8:9], s[8:9], 0x100000
	s_ashr_i32 s21, s20, 31
	v_writelane_b32 v252, s11, 60
	s_lshl_b64 s[8:9], s[8:9], 19
	s_lshl_b64 s[10:11], s[20:21], 19
	v_writelane_b32 v252, s8, 61
	s_mul_i32 s12, s31, s30
	s_mul_i32 s5, s12, s33
	v_writelane_b32 v252, s9, 62
	s_add_u32 s8, s46, s10
	s_addc_u32 s9, s47, s11
	s_add_u32 s10, s8, 0x40000
	v_writelane_b32 v252, s8, 63
	s_addc_u32 s11, s9, 0
	s_ashr_i32 s77, s30, 31
	v_writelane_b32 v253, s9, 0
	v_writelane_b32 v253, s10, 1
	s_cmp_lt_u32 s81, 64
	s_cselect_b64 s[8:9], -1, 0
	v_writelane_b32 v253, s11, 2
	v_writelane_b32 v253, s8, 3
	s_waitcnt vmcnt(4)
	v_or_b32_e32 v0, v188, v187
	s_mov_b32 s13, 0
	v_writelane_b32 v253, s9, 4
	s_add_u32 s8, s26, 0x180200
	v_writelane_b32 v253, s5, 5
	s_addc_u32 s9, s27, 0
	v_writelane_b32 v253, s8, 6
	s_movk_i32 s5, 0x3ff
	v_and_or_b32 v0, v0, s5, v186
	v_writelane_b32 v253, s9, 7
	s_add_u32 s8, s26, 0x180400
	s_addc_u32 s9, s27, 0
	v_writelane_b32 v253, s8, 8
	v_mbcnt_hi_u32_b32 v228, -1, v129
	s_mov_b32 s72, 2
	v_writelane_b32 v253, s9, 9
	s_add_u32 s8, s26, 0x180500
	s_addc_u32 s9, s27, 0
	v_writelane_b32 v253, s8, 10
	v_mov_b32_e32 v193, 0
	s_movk_i32 s33, 0x4000
	v_writelane_b32 v253, s9, 11
	s_add_u32 s8, s26, 0x180600
	s_addc_u32 s9, s27, 0
	v_writelane_b32 v253, s8, 12
	s_mov_b64 s[68:69], 0x80
	v_mov_b32_e32 v222, 0x358637bd
	v_writelane_b32 v253, s9, 13
	s_add_u32 s8, s26, 0x180700
	s_addc_u32 s9, s27, 0
	v_writelane_b32 v253, s8, 14
	s_mov_b32 s45, 0x800000
	s_mov_b32 s44, 0x3fb8aa3b
	v_writelane_b32 v253, s9, 15
	s_add_u32 s8, s26, 0x180800
	s_addc_u32 s9, s27, 0
	v_writelane_b32 v253, s8, 16
	s_mov_b32 s36, 0x3f317218
	s_movk_i32 s31, 0x1600
	v_writelane_b32 v253, s9, 17
	s_add_u32 s8, s26, 0x180900
	s_addc_u32 s9, s27, 0
	v_writelane_b32 v253, s8, 18
	s_mov_b32 s34, 0x1f800000
	v_mov_b64_e32 v[194:195], 0x200
	v_writelane_b32 v253, s9, 19
	s_add_u32 s8, s26, 0x180a00
	s_addc_u32 s9, s27, 0
	v_writelane_b32 v253, s8, 20
	s_waitcnt lgkmcnt(7)
	v_mov_b64_e32 v[196:197], 0x1ff
	v_writelane_b32 v253, s9, 21
	s_add_u32 s8, s26, 0x180b00
	s_addc_u32 s9, s27, 0
	v_writelane_b32 v253, s8, 22
	s_nop 1
	v_writelane_b32 v253, s9, 23
	s_add_u32 s8, s26, 0x180c00
	s_addc_u32 s9, s27, 0
	v_writelane_b32 v253, s8, 24
	s_nop 1
	v_writelane_b32 v253, s9, 25
	s_add_u32 s8, s26, 0x180d00
	s_addc_u32 s9, s27, 0
	v_writelane_b32 v253, s8, 26
	s_nop 1
	v_writelane_b32 v253, s9, 27
	s_add_u32 s8, s26, 0x180e00
	s_addc_u32 s9, s27, 0
	v_writelane_b32 v253, s8, 28
	s_nop 1
	v_writelane_b32 v253, s9, 29
	s_add_u32 s8, s26, 0x180f00
	s_addc_u32 s9, s27, 0
	v_writelane_b32 v253, s8, 30
	s_nop 1
	v_writelane_b32 v253, s9, 31
	s_add_u32 s8, s26, 0x181000
	s_addc_u32 s9, s27, 0
	v_writelane_b32 v253, s8, 32
	s_nop 1
	v_writelane_b32 v253, s9, 33
	s_add_u32 s8, s26, 0x181100
	s_addc_u32 s9, s27, 0
	v_writelane_b32 v253, s8, 34
	s_nop 1
	v_writelane_b32 v253, s9, 35
	s_add_u32 s8, s26, 0x181200
	s_addc_u32 s9, s27, 0
	v_writelane_b32 v253, s8, 36
	s_nop 1
	v_writelane_b32 v253, s9, 37
	s_add_u32 s8, s26, 0x181300
	s_addc_u32 s9, s27, 0
	v_writelane_b32 v253, s8, 38
	s_nop 1
	v_writelane_b32 v253, s9, 39
	s_add_u32 s8, s26, 0x183400
	s_addc_u32 s9, s27, 0
	v_writelane_b32 v253, s8, 40
	s_nop 1
	v_writelane_b32 v253, s9, 41
	s_add_u32 s8, s26, 0x183500
	s_addc_u32 s9, s27, 0
	v_writelane_b32 v253, s8, 42
	s_add_u32 s20, s26, 0x21600000
	s_addc_u32 s21, s27, 0
	v_writelane_b32 v253, s9, 43
	v_cmp_eq_u32_e64 s[8:9], 0, v0
	s_cmpk_lt_i32 s2, 0x400
	s_nop 0
	v_writelane_b32 v253, s8, 44
	s_nop 1
	v_writelane_b32 v253, s9, 45
	s_cselect_b64 s[8:9], -1, 0
	v_writelane_b32 v253, s8, 46
	s_cmpk_lt_i32 s2, 0x100
	s_nop 0
	v_writelane_b32 v253, s9, 47
	s_cselect_b64 s[8:9], -1, 0
; __device__ __forceinline__ void sb_attn_wave(const bf16_t* __restrict__ P, const bf16_t* __restrict__ KHp, const bf16_t* __restrict__ Vt, bf16_t* __restrict__ mixed, int gw, int NGW, int lane, LAS unsigned char* wl) {
;     ...
;     int u = gw; if (u >= NUNITS) return;
;     size_t tok0; int q0, h, kt; const bf16_t* kg; const bf16_t* vg;
;     bf16x8 qf[4]; u32x4 ks[8], vs[8];
;     ...
;     SB_UNIT_SETUP(u);
; __global__ void __launch_bounds__(512, 2) fwd_kernel(Args a) {
;     ...
;                     for (int u = gw; u < MTOK / 16; u += NGW) convpool_unit(PROJ, MIX, a.in[12] + (size_t)l * 768, u, lane);
	s_lshl_b32 s5, s2, 3
	s_add_i32 s12, s3, s5
	s_bfe_u32 s5, s12, 0x10002
	s_xor_b32 s12, s12, s5
	v_writelane_b32 v253, s8, 48
	s_cmpk_lt_i32 s12, 0x2000
	s_mul_i32 s5, s3, 0x4800
	v_writelane_b32 v253, s9, 49
	s_cselect_b64 s[8:9], -1, 0
	v_writelane_b32 v253, s8, 50
	s_add_i32 s5, s5, 0
	s_ashr_i32 s10, s12, 10
	v_writelane_b32 v253, s9, 51
	v_writelane_b32 v253, s5, 52
	s_ashr_i32 s11, s10, 31
	s_lshl_b32 s5, s12, 5
	s_lshl_b64 s[10:11], s[10:11], 12
	s_and_b32 s14, s5, 0xfe0
	v_writelane_b32 v253, s14, 53
	s_or_b32 s14, s10, s14
	v_writelane_b32 v253, s14, 54
	v_writelane_b32 v253, s10, 55
	s_ashr_i32 s8, s12, 7
	s_and_b32 s9, s8, 7
	v_writelane_b32 v253, s11, 56
	s_mov_b32 s10, s11
	v_writelane_b32 v253, s10, 57
	v_writelane_b32 v253, s9, 58
	s_lshl_b32 s9, s9, 7
	s_add_u32 s10, s16, s9
	s_addc_u32 s11, s17, 0
	s_ashr_i32 s9, s8, 31
	v_writelane_b32 v253, s10, 59
	s_lshl_b64 s[8:9], s[8:9], 19
	s_nop 0
	v_writelane_b32 v253, s11, 60
	s_add_u32 s10, s18, s8
	s_addc_u32 s11, s19, s9
	s_bfe_u32 s5, s5, 0x60006
	v_writelane_b32 v253, s10, 61
	s_add_u32 s8, s20, s8
	s_addc_u32 s9, s21, s9
	v_writelane_b32 v253, s11, 62
	v_writelane_b32 v253, s8, 63
	s_nop 1
	v_writelane_b32 v254, s9, 0
	v_writelane_b32 v254, s5, 1
	s_lshl_b32 s5, s5, 12
	s_cmpk_lt_i32 s12, 0x800
	v_writelane_b32 v254, s12, 2
	s_cselect_b64 s[8:9], -1, 0
	v_writelane_b32 v254, s8, 3
	s_nop 1
	v_writelane_b32 v254, s9, 4
	s_add_u32 s8, s26, 0xe200a00
	s_addc_u32 s9, s27, 0
	v_writelane_b32 v254, s8, 5
	s_nop 1
	v_writelane_b32 v254, s9, 6
	s_add_u32 s8, s26, 0xe200c00
	s_addc_u32 s9, s27, 0
	v_writelane_b32 v254, s8, 7
	s_nop 1
	v_writelane_b32 v254, s9, 8
	s_add_u32 s8, s26, 0xe200800
	s_addc_u32 s9, s27, 0
	v_writelane_b32 v254, s8, 9
	s_nop 1
	v_writelane_b32 v254, s9, 10
	s_add_u32 s8, s26, 0xe200e00
	s_addc_u32 s9, s27, 0
	v_writelane_b32 v254, s8, 11
	s_cmpk_lt_i32 s2, 0x200
	s_nop 0
	v_writelane_b32 v254, s9, 12
	s_cselect_b64 s[8:9], -1, 0
	v_writelane_b32 v254, s8, 13
	s_add_i32 s0, s0, s7
	s_add_i32 s4, s4, s7
	v_writelane_b32 v254, s9, 14
	s_ashr_i32 s8, s0, 31
	s_lshr_b32 s8, s8, 26
	s_add_i32 s8, s0, s8
	s_ashr_i32 s9, s8, 6
	s_and_b32 s8, s8, 0xffc0
	s_sub_i32 s8, s0, s8
	s_bfe_i32 s0, s8, 0x80000
	s_bfe_u32 s0, s0, 0x3000c
	s_add_i32 s10, s8, s0
	s_bfe_i32 s0, s10, 0x80000
	s_and_b32 s10, s10, 0xf8
	s_sub_i32 s8, s8, s10
	s_lshl_b32 s9, s9, 3
	s_sext_i32_i8 s8, s8
	s_add_i32 s22, s9, s8
	s_add_i32 s9, s6, s7
	s_ashr_i32 s6, s9, 31
	s_lshr_b32 s6, s6, 22
	s_ashr_i32 s7, s4, 31
	s_add_i32 s10, s9, s6
	s_lshr_b32 s7, s7, 27
	s_ashr_i32 s6, s10, 10
	s_and_b32 s10, s10, 0xfffffc00
	s_add_i32 s7, s4, s7
	s_sub_i32 s9, s9, s10
	s_ashr_i32 s10, s7, 5
	s_and_b32 s7, s7, 0xffe0
	s_sub_i32 s7, s4, s7
	s_bfe_i32 s4, s7, 0x80000
	s_sext_i32_i16 s11, s0
	s_bfe_u32 s4, s4, 0x3000c
	s_lshr_b32 s0, s11, 3
	s_ashr_i32 s8, s11, 3
	s_add_i32 s11, s7, s4
	s_bfe_i32 s4, s11, 0x80000
	s_and_b32 s11, s11, 0xf8
	s_sub_i32 s7, s7, s11
	s_lshl_b32 s10, s10, 3
	s_sext_i32_i8 s7, s7
	v_writelane_b32 v254, s8, 15
	s_sext_i32_i16 s12, s4
	s_add_i32 s7, s10, s7
	s_lshl_b32 s6, s6, 3
	v_writelane_b32 v254, s7, 16
	s_ashr_i32 s7, s12, 3
	s_sub_i32 s8, 2, s6
	v_writelane_b32 v254, s7, 17
	s_mov_b32 s10, s22
	s_min_u32 s8, s8, 8
	s_ashr_i32 s23, s22, 31
	v_writelane_b32 v254, s10, 18
	v_cvt_f32_ubyte0_e32 v1, s8
	s_lshr_b32 s4, s12, 3
	v_writelane_b32 v254, s11, 19
	s_lshl_b64 s[10:11], s[22:23], 19
	s_bfe_i64 s[22:23], s[0:1], 0x100000
	s_lshl_b64 s[22:23], s[22:23], 19
	v_cvt_f32_i32_e32 v0, s9
	v_rcp_iflag_f32_e32 v2, v1
	v_writelane_b32 v254, s22, 20
	s_add_u32 s10, s46, s10
	s_addc_u32 s11, s47, s11
	v_writelane_b32 v254, s23, 21
	s_add_u32 s22, s10, 0x40000
	v_writelane_b32 v254, s10, 22
	s_addc_u32 s23, s11, 0
	v_mul_f32_e32 v2, v0, v2
	v_writelane_b32 v254, s11, 23
	v_writelane_b32 v254, s22, 24
	v_trunc_f32_e32 v2, v2
	s_bfe_i64 s[10:11], s[4:5], 0x100000
	v_writelane_b32 v254, s23, 25
	v_fma_f32 v0, -v2, v1, v0
	v_cvt_i32_f32_e32 v2, v2
	v_writelane_b32 v254, s10, 26
	s_ashr_i32 s0, s9, 30
	s_or_b32 s0, s0, 1
	v_writelane_b32 v254, s11, 27
	v_cmp_ge_f32_e64 s[10:11], |v0|, v1
	s_and_b64 s[10:11], s[10:11], exec
	s_cselect_b32 s0, s0, 0
	v_readfirstlane_b32 s4, v2
	s_add_i32 s0, s4, s0
	s_sext_i32_i16 s4, s0
	v_writelane_b32 v254, s4, 28
	s_mul_i32 s4, s0, s8
	s_sub_i32 s4, s9, s4
	s_sext_i32_i16 s4, s4
	s_add_i32 s6, s6, s4
	s_mov_b32 s4, s6
	s_ashr_i32 s7, s6, 31
	v_writelane_b32 v254, s4, 29
	s_lshl_b64 s[6:7], s[6:7], 19
	s_nop 0
	v_writelane_b32 v254, s5, 30
	v_writelane_b32 v254, s6, 31
	s_nop 1
	v_writelane_b32 v254, s7, 32
	s_bfe_i64 s[6:7], s[0:1], 0x100000
	s_lshl_b64 s[6:7], s[6:7], 19
	s_add_u32 s6, s46, s6
	s_addc_u32 s7, s47, s7
	s_add_u32 s8, s6, 0x40000
	s_addc_u32 s9, s7, 0
	v_writelane_b32 v254, s8, 33
	s_nop 1
	v_writelane_b32 v254, s9, 34
	s_add_u32 s8, s6, 0x40080
	v_writelane_b32 v254, s6, 35
	s_addc_u32 s9, s7, 0
	s_lshl_b32 s0, s2, 7
	v_writelane_b32 v254, s7, 36
	s_lshl_b32 s3, s3, 4
	v_writelane_b32 v254, s8, 37
	s_add_i32 s0, s0, s3
	s_add_i32 s0, s0, -16
	v_writelane_b32 v254, s9, 38
	v_writelane_b32 v254, s0, 39
	s_add_i32 s0, 0, 0x20000
	v_writelane_b32 v254, s0, 40
	s_add_i32 s0, 0, 0x24000
	v_writelane_b32 v254, s0, 41
	s_add_i32 s0, 0, 0x24004
	v_writelane_b32 v254, s0, 42
	s_lshl_b32 s0, s5, 1
	v_writelane_b32 v254, s0, 43
	s_lshl_b32 s12, s30, 7
	s_mov_b32 s6, s13
	v_writelane_b32 v254, s1, 44
	s_add_i32 s0, 0, 0x21000
	v_writelane_b32 v254, s0, 45
	v_writelane_b32 v254, s64, 46
	v_add_u32_e32 v223, s1, v228
	s_nop 0
	v_writelane_b32 v254, s65, 47
	v_writelane_b32 v254, s12, 48
	s_branch .LBB0_152
